# attention QK^T: the ten key-tile steps of a query tile pipelined (one address + immediate offsets, K fragments of five key tiles in flight in spare registers, scores accumulated in place)
# speedup vs baseline: 1.0061x; 1.0044x over previous
; #define LAS __attribute__((address_space(3)))
; __device__ __forceinline__ void attn_phase(LAS unsigned char* lds, const bf16_t* QKVZ, const float* sinks, bf16_t* OG, int G, int bid, int tid) {
;     ...
;         for (int mt = 0; mt < 4; ++mt) {
;             const int qo0 = qh * 64 + mt * 16;
;             const size_t row = (size_t)(b * T + n * 128 + qo0 + fr);
;             const bf16_t* qp = QKVZ + row * ATT_IN + h * 64 + fq * 8;
;             const bf16x8 q0 = *(const bf16x8*)qp, q1 = *(const bf16x8*)(qp + 32);
;             const int kt0 = (qh * 4 + mt) < 6 ? (qh * 4 + mt) : 6;
;             f32x4 s[10];
; #pragma unroll
;             for (int kt = 0; kt < 10; ++kt) {
;                 const LAS unsigned char* kp = Kl + ((kt0 + kt) * 16 + fr) * KP + fq * 16;
;                 const bf16x8 k0 = *(const LAS bf16x8*)kp, k1 = *(const LAS bf16x8*)(kp + 64);
;                 f32x4 acc = (f32x4){0.f, 0.f, 0.f, 0.f};
;                 acc = __builtin_amdgcn_mfma_f32_16x16x32_bf16(k0, q0, acc, 0, 0, 0);
;                 acc = __builtin_amdgcn_mfma_f32_16x16x32_bf16(k1, q1, acc, 0, 0, 0);
;                 s[kt] = acc;
;             }
.Lmy_att_t0:
	v_add_u32_e32 v82, s1, v140
	v_mov_b64_e32 v[32:33], s[14:15]
	v_mad_i64_i32 v[84:85], s[26:27], v82, s22, v[32:33]
	v_lshl_add_u64 v[36:37], v[84:85], 0, v[72:73]
	v_mov_b64_e32 v[32:33], v[186:187]
	v_mov_b64_e32 v[34:35], v[188:189]
	v_mov_b64_e32 v[162:163], v[190:191]
	v_mov_b64_e32 v[164:165], v[192:193]
	s_mov_b32 s99, 0x14000
	s_cmp_eq_u32 s1, 48
	s_cselect_b32 s99, 0x27c4000, s99
	v_add_co_u32_e32 v194, vcc, s99, v36
	s_nop 1
	v_addc_co_u32_e32 v195, vcc, 0, v37, vcc
	global_load_dwordx4 v[186:189], v[194:195], off
	global_load_dwordx4 v[190:193], v[194:195], off offset:64
	v_lshlrev_b32_e32 v196, 1, v76
	v_mov_b32_e32 v197, v73
	v_lshl_add_u64 v[198:199], v[84:85], 0, v[196:197]
	global_load_dwordx2 v[200:201], v[198:199], off offset:3072
	global_load_dwordx2 v[202:203], v[198:199], off offset:3104
	global_load_dwordx2 v[204:205], v[198:199], off offset:3136
	global_load_dwordx2 v[206:207], v[198:199], off offset:3168
	s_min_u32 s25, s8, 6
	s_lshl_b32 s25, s25, 4
	s_add_i32 s26, s25, 16
	s_add_i32 s29, s25, 32
	s_add_i32 s28, s25, 64
	s_add_i32 s27, s25, 0x60
	s_add_i32 s30, s25, 0x90
	s_add_i32 s26, s25, 48
	s_add_i32 s26, s25, 0x50
	s_add_i32 s26, s25, 0x70
	s_or_b32 s26, s25, 0x80
	v_or_b32_e32 v248, s25, v89
	v_mad_u32_u24 v248, v248, s19, v90
	ds_read_b128 v[208:211], v248
	ds_read_b128 v[212:215], v248 offset:64
	ds_read_b128 v[216:219], v248 offset:2304
	ds_read_b128 v[220:223], v248 offset:2368
	ds_read_b128 v[224:227], v248 offset:4608
	ds_read_b128 v[228:231], v248 offset:4672
	ds_read_b128 v[232:235], v248 offset:6912
	ds_read_b128 v[236:239], v248 offset:6976
	ds_read_b128 v[240:243], v248 offset:9216
	ds_read_b128 v[244:247], v248 offset:9280
	v_subrev_u32_e32 v185, s25, v129
	v_add_u32_e32 v146, s25, v139
	v_subrev_u32_e32 v180, s25, v118
	v_subrev_u32_e32 v179, s25, v117
	v_subrev_u32_e32 v184, s25, v128
	v_subrev_u32_e32 v178, s25, v116
	v_subrev_u32_e32 v175, s25, v107
	v_subrev_u32_e32 v183, s25, v127
	v_subrev_u32_e32 v177, s25, v115
	v_subrev_u32_e32 v174, s25, v106
	v_subrev_u32_e32 v182, s25, v126
	v_subrev_u32_e32 v176, s25, v114
	v_subrev_u32_e32 v161, s25, v105
	v_subrev_u32_e32 v181, s25, v125
	v_subrev_u32_e32 v159, s25, v113
	v_subrev_u32_e32 v158, s25, v104
	v_subrev_u32_e32 v160, s25, v124
	v_subrev_u32_e32 v156, s25, v112
	v_subrev_u32_e32 v155, s25, v103
	v_subrev_u32_e32 v157, s25, v123
	v_subrev_u32_e32 v152, s25, v111
	v_subrev_u32_e32 v151, s25, v102
	v_subrev_u32_e32 v153, s25, v122
	v_subrev_u32_e32 v149, s25, v110
	v_subrev_u32_e32 v147, s25, v101
	v_subrev_u32_e32 v150, s25, v121
	v_subrev_u32_e32 v145, s25, v109
	v_subrev_u32_e32 v144, s25, v100
	v_subrev_u32_e32 v148, s25, v120
	v_subrev_u32_e32 v143, s25, v108
	v_subrev_u32_e32 v142, s25, v98
	v_ashrrev_i32_e32 v83, 31, v82
	v_add_u32_e32 v139, -16, v139
	s_waitcnt lgkmcnt(8)
	v_mfma_f32_16x16x32_bf16 v[68:71], v[208:211], v[32:35], 0
	v_mfma_f32_16x16x32_bf16 v[68:71], v[212:215], v[162:165], v[68:71]
	s_waitcnt lgkmcnt(6)
	v_mfma_f32_16x16x32_bf16 v[64:67], v[216:219], v[32:35], 0
	v_mfma_f32_16x16x32_bf16 v[64:67], v[220:223], v[162:165], v[64:67]
	ds_read_b128 v[208:211], v248 offset:11520
	ds_read_b128 v[212:215], v248 offset:11584
	s_waitcnt lgkmcnt(6)
	v_mfma_f32_16x16x32_bf16 v[60:63], v[224:227], v[32:35], 0
	v_mfma_f32_16x16x32_bf16 v[60:63], v[228:231], v[162:165], v[60:63]
	ds_read_b128 v[216:219], v248 offset:13824
	ds_read_b128 v[220:223], v248 offset:13888
	s_waitcnt lgkmcnt(6)
	v_mfma_f32_16x16x32_bf16 v[56:59], v[232:235], v[32:35], 0
	v_mfma_f32_16x16x32_bf16 v[56:59], v[236:239], v[162:165], v[56:59]
	ds_read_b128 v[224:227], v248 offset:16128
	ds_read_b128 v[228:231], v248 offset:16192
	s_waitcnt lgkmcnt(6)
	v_mfma_f32_16x16x32_bf16 v[52:55], v[240:243], v[32:35], 0
	v_mfma_f32_16x16x32_bf16 v[52:55], v[244:247], v[162:165], v[52:55]
	ds_read_b128 v[232:235], v248 offset:18432
	ds_read_b128 v[236:239], v248 offset:18496
	s_waitcnt lgkmcnt(6)
	v_mfma_f32_16x16x32_bf16 v[48:51], v[208:211], v[32:35], 0
	v_mfma_f32_16x16x32_bf16 v[48:51], v[212:215], v[162:165], v[48:51]
	ds_read_b128 v[240:243], v248 offset:20736
	ds_read_b128 v[244:247], v248 offset:20800
	s_waitcnt lgkmcnt(6)
	v_mfma_f32_16x16x32_bf16 v[44:47], v[216:219], v[32:35], 0
	v_mfma_f32_16x16x32_bf16 v[44:47], v[220:223], v[162:165], v[44:47]
	s_waitcnt lgkmcnt(4)
	v_mfma_f32_16x16x32_bf16 v[40:43], v[224:227], v[32:35], 0
	v_mfma_f32_16x16x32_bf16 v[40:43], v[228:231], v[162:165], v[40:43]
	s_waitcnt lgkmcnt(2)
	v_mfma_f32_16x16x32_bf16 v[36:39], v[232:235], v[32:35], 0
	v_mfma_f32_16x16x32_bf16 v[36:39], v[236:239], v[162:165], v[36:39]
	s_waitcnt lgkmcnt(0)
; #define LAS __attribute__((address_space(3)))
; __device__ __forceinline__ void attn_phase(LAS unsigned char* lds, const bf16_t* QKVZ, const float* sinks, bf16_t* OG, int G, int bid, int tid) {
;     ...
;             for (int kt = 0; kt < 10; ++kt) {
;                 const LAS unsigned char* kp = Kl + ((kt0 + kt) * 16 + fr) * KP + fq * 16;
;                 const bf16x8 k0 = *(const LAS bf16x8*)kp, k1 = *(const LAS bf16x8*)(kp + 64);
;                 f32x4 acc = (f32x4){0.f, 0.f, 0.f, 0.f};
;                 acc = __builtin_amdgcn_mfma_f32_16x16x32_bf16(k0, q0, acc, 0, 0, 0);
;                 acc = __builtin_amdgcn_mfma_f32_16x16x32_bf16(k1, q1, acc, 0, 0, 0);
;                 s[kt] = acc;
;             }
;             const int qi = 128 + qo0 + fr;
;             float mx = sink2;
; #pragma unroll
;             for (int kt = 0; kt < 10; ++kt)
; #pragma unroll
;                 for (int r = 0; r < 4; ++r) { const int si = (kt0 + kt) * 16 + 4 * fq + r, df = qi - si; const bool ok = (df >= 0) && (df < 128) && (n > 0 || si >= 128);
;                     const float v = ok ? s[kt][r] : -1e30f; s[kt][r] = v; mx = fmaxf(mx, v); }
;             mx = fmaxf(mx, __shfl_xor(mx, 16)); mx = fmaxf(mx, __shfl_xor(mx, 32));
	v_mfma_f32_16x16x32_bf16 v[32:35], v[240:243], v[32:35], 0
	v_mfma_f32_16x16x32_bf16 v[32:35], v[244:247], v[162:165], v[32:35]
	v_or_b32_e32 v154, s25, v76
	v_add_u32_e32 v162, s1, v99
	v_add_u32_e32 v163, v162, v185
	v_cmp_gt_u32_e32 vcc, s20, v163
	s_and_b64 vcc, s[12:13], vcc
	v_add_u32_e32 v163, 0xffffff80, v146
	v_cndmask_b32_e32 v68, v138, v68, vcc
	v_cmp_lt_u32_e32 vcc, s23, v163
	s_and_b64 vcc, s[12:13], vcc
	v_add_u32_e32 v164, v162, v180
	v_cndmask_b32_e32 v69, v138, v69, vcc
	v_cmp_gt_u32_e32 vcc, s20, v164
	s_and_b64 vcc, s[12:13], vcc
	v_add_u32_e32 v164, v162, v179
	v_cndmask_b32_e32 v70, v138, v70, vcc
	v_cmp_gt_u32_e32 vcc, s20, v164
	s_and_b64 vcc, s[12:13], vcc
	v_add_u32_e32 v164, v162, v184
	v_cndmask_b32_e32 v71, v138, v71, vcc
	v_cmp_gt_u32_e32 vcc, s20, v164
	s_and_b64 vcc, s[12:13], vcc
	v_add_u32_e32 v164, 0xffffff90, v146
	v_cndmask_b32_e32 v64, v138, v64, vcc
	v_cmp_lt_u32_e32 vcc, s23, v164
	s_and_b64 vcc, s[12:13], vcc
	v_add_u32_e32 v164, v162, v178
	v_cndmask_b32_e32 v65, v138, v65, vcc
	v_cmp_gt_u32_e32 vcc, s20, v164
	s_and_b64 vcc, s[12:13], vcc
	v_add_u32_e32 v164, v162, v175
	v_cndmask_b32_e32 v66, v138, v66, vcc
	v_cmp_gt_u32_e32 vcc, s20, v164
	s_and_b64 vcc, s[12:13], vcc
	s_cmp_gt_u32 s8, 5
	v_add_u32_e32 v165, v162, v183
	s_cselect_b64 s[30:31], -1, 0
	v_cndmask_b32_e32 v67, v138, v67, vcc
	v_cmp_gt_u32_e32 vcc, s20, v165
	s_or_b64 s[30:31], s[12:13], s[30:31]
	s_and_b64 vcc, vcc, s[30:31]
	v_add_u32_e32 v165, 0xffffffa0, v146
	v_cndmask_b32_e32 v60, v138, v60, vcc
	v_cmp_lt_u32_e32 vcc, s23, v165
	s_and_b64 vcc, vcc, s[30:31]
	v_add_u32_e32 v165, v162, v177
	v_cndmask_b32_e32 v61, v138, v61, vcc
	v_cmp_gt_u32_e32 vcc, s20, v165
	s_and_b64 vcc, vcc, s[30:31]
	v_add_u32_e32 v165, v162, v174
	v_cndmask_b32_e32 v62, v138, v62, vcc
	v_cmp_gt_u32_e32 vcc, s20, v165
	s_and_b64 vcc, vcc, s[30:31]
	s_cmp_gt_u32 s8, 4
	v_add_u32_e32 v165, v162, v182
	s_cselect_b64 s[30:31], -1, 0
	v_cndmask_b32_e32 v63, v138, v63, vcc
	v_cmp_gt_u32_e32 vcc, s20, v165
	s_or_b64 s[30:31], s[12:13], s[30:31]
	s_and_b64 vcc, vcc, s[30:31]
	v_add_u32_e32 v165, 0xffffffb0, v146
	v_cndmask_b32_e32 v56, v138, v56, vcc
	v_cmp_lt_u32_e32 vcc, s23, v165
	s_and_b64 vcc, vcc, s[30:31]
	v_add_u32_e32 v165, v162, v176
	v_cndmask_b32_e32 v57, v138, v57, vcc
	v_cmp_gt_u32_e32 vcc, s20, v165
	s_and_b64 vcc, vcc, s[30:31]
	v_add_u32_e32 v161, v162, v161
	v_cndmask_b32_e32 v58, v138, v58, vcc
	v_cmp_gt_u32_e32 vcc, s20, v161
	s_and_b64 vcc, vcc, s[30:31]
	s_cmp_gt_u32 s8, 3
	v_add_u32_e32 v165, v162, v181
	s_cselect_b64 s[30:31], -1, 0
	v_cndmask_b32_e32 v59, v138, v59, vcc
	v_cmp_gt_u32_e32 vcc, s20, v165
	s_or_b64 s[30:31], s[12:13], s[30:31]
	s_and_b64 vcc, vcc, s[30:31]
	v_subrev_u32_e32 v165, 64, v146
	v_cndmask_b32_e32 v52, v138, v52, vcc
	v_cmp_lt_u32_e32 vcc, s23, v165
	s_and_b64 vcc, vcc, s[30:31]
	v_add_u32_e32 v159, v162, v159
	v_cndmask_b32_e32 v53, v138, v53, vcc
	v_cmp_gt_u32_e32 vcc, s20, v159
	s_and_b64 vcc, vcc, s[30:31]
	v_add_u32_e32 v158, v162, v158
	v_cndmask_b32_e32 v54, v138, v54, vcc
	v_cmp_gt_u32_e32 vcc, s20, v158
	s_and_b64 vcc, vcc, s[30:31]
	s_cmp_gt_u32 s8, 2
	v_add_u32_e32 v159, v162, v160
	s_cselect_b64 s[30:31], -1, 0
	v_cndmask_b32_e32 v55, v138, v55, vcc
	v_cmp_gt_u32_e32 vcc, s20, v159
	s_or_b64 s[30:31], s[12:13], s[30:31]
	s_and_b64 vcc, vcc, s[30:31]
	v_subrev_u32_e32 v159, 48, v146
	v_cndmask_b32_e32 v48, v138, v48, vcc
	v_cmp_lt_u32_e32 vcc, s23, v159
	s_and_b64 vcc, vcc, s[30:31]
	v_add_u32_e32 v156, v162, v156
	v_cndmask_b32_e32 v49, v138, v49, vcc
	v_cmp_gt_u32_e32 vcc, s20, v156
	s_and_b64 vcc, vcc, s[30:31]
	v_add_u32_e32 v155, v162, v155
	v_cndmask_b32_e32 v50, v138, v50, vcc
	v_cmp_gt_u32_e32 vcc, s20, v155
	s_and_b64 vcc, vcc, s[30:31]
	s_cmp_gt_u32 s8, 1
	v_add_u32_e32 v157, v162, v157
	s_cselect_b64 s[30:31], -1, 0
	v_cndmask_b32_e32 v51, v138, v51, vcc
	v_cmp_gt_u32_e32 vcc, s20, v157
	s_or_b64 s[30:31], s[12:13], s[30:31]
	s_and_b64 vcc, vcc, s[30:31]
	v_subrev_u32_e32 v157, 32, v146
	v_cndmask_b32_e32 v44, v138, v44, vcc
	v_cmp_lt_u32_e32 vcc, s23, v157
	s_and_b64 vcc, vcc, s[30:31]
	v_add_u32_e32 v152, v162, v152
	v_cndmask_b32_e32 v45, v138, v45, vcc
	v_cmp_gt_u32_e32 vcc, s20, v152
	s_and_b64 vcc, vcc, s[30:31]
	v_add_u32_e32 v151, v162, v151
	v_cndmask_b32_e32 v46, v138, v46, vcc
	v_cmp_gt_u32_e32 vcc, s20, v151
	v_max3_f32 v163, v141, v68, v69
	s_and_b64 vcc, vcc, s[30:31]
	s_or_b32 s30, s8, s0
	v_max3_f32 v163, v163, v70, v71
	v_add_u32_e32 v152, v162, v153
	s_cmp_lg_u32 s30, 0
	v_max3_f32 v163, v163, v64, v65
	v_cndmask_b32_e32 v47, v138, v47, vcc
	v_cmp_gt_u32_e32 vcc, s20, v152
	s_cselect_b64 s[30:31], -1, 0
	v_max3_f32 v163, v163, v66, v67
	s_and_b64 vcc, s[30:31], vcc
	v_add_u32_e32 v152, -16, v146
	v_max3_f32 v163, v163, v60, v61
	v_cndmask_b32_e32 v40, v138, v40, vcc
	v_cmp_lt_u32_e32 vcc, s23, v152
	v_max3_f32 v163, v163, v62, v63
	s_and_b64 vcc, s[30:31], vcc
	v_add_u32_e32 v149, v162, v149
	v_max3_f32 v163, v163, v56, v57
	v_cndmask_b32_e32 v41, v138, v41, vcc
	v_cmp_gt_u32_e32 vcc, s20, v149
	v_max3_f32 v161, v163, v58, v59
	s_and_b64 vcc, s[30:31], vcc
	v_add_u32_e32 v147, v162, v147
	v_max3_f32 v161, v161, v52, v53
	v_cndmask_b32_e32 v42, v138, v42, vcc
	v_cmp_gt_u32_e32 vcc, s20, v147
	v_max3_f32 v158, v161, v54, v55
	s_and_b64 vcc, s[30:31], vcc
	v_add_u32_e32 v150, v162, v150
	v_max3_f32 v158, v158, v48, v49
	v_cndmask_b32_e32 v43, v138, v43, vcc
	v_cmp_gt_u32_e32 vcc, s20, v150
	v_max3_f32 v155, v158, v50, v51
	v_add_u32_e32 v145, v162, v145
	v_cndmask_b32_e32 v36, v138, v36, vcc
	v_cmp_lt_u32_e32 vcc, s23, v146
	v_max3_f32 v155, v155, v44, v45
	v_add_u32_e32 v144, v162, v144
	v_cndmask_b32_e32 v37, v138, v37, vcc
	v_cmp_gt_u32_e32 vcc, s20, v145
	v_max3_f32 v151, v155, v46, v47
	v_add_u32_e32 v145, v162, v148
	v_cndmask_b32_e32 v38, v138, v38, vcc
	v_cmp_gt_u32_e32 vcc, s20, v144
	v_max3_f32 v151, v151, v40, v41
	v_max3_f32 v147, v151, v42, v43
	v_cndmask_b32_e32 v39, v138, v39, vcc
	v_cmp_gt_u32_e32 vcc, s20, v145
	v_add_u32_e32 v145, 16, v146
	v_add_u32_e32 v143, v162, v143
	v_cndmask_b32_e32 v32, v138, v32, vcc
	v_cmp_lt_u32_e32 vcc, s23, v145
	v_max3_f32 v147, v147, v36, v37
	v_add_u32_e32 v142, v162, v142
	v_cndmask_b32_e32 v33, v138, v33, vcc
	v_cmp_gt_u32_e32 vcc, s20, v143
	v_max3_f32 v144, v147, v38, v39
	v_max3_f32 v144, v144, v32, v33
	v_cndmask_b32_e32 v34, v138, v34, vcc
	v_cmp_gt_u32_e32 vcc, s20, v142
	v_or_b32_e32 v164, s29, v76
	v_or_b32_e32 v163, s28, v76
	v_cndmask_b32_e32 v35, v138, v35, vcc
	v_max3_f32 v142, v144, v34, v35
	ds_bpermute_b32 v143, v91, v142
	v_or_b32_e32 v156, s27, v76
	v_or_b32_e32 v149, s26, v76
	s_add_i32 s1, s1, 16
	s_add_i32 s8, s8, 1
	s_waitcnt lgkmcnt(0)
; __device__ __forceinline__ u32x4 pack8(const f32x4 a, const f32x4 b) { u32x4 w; w.x = cvt_pk_bf16(a[0], a[1]); w.y = cvt_pk_bf16(a[2], a[3]); w.z = cvt_pk_bf16(b[0], b[1]); w.w = cvt_pk_bf16(b[2], b[3]); return w; }
; #define LAS __attribute__((address_space(3)))
; __device__ __forceinline__ void attn_phase(LAS unsigned char* lds, const bf16_t* QKVZ, const float* sinks, bf16_t* OG, int G, int bid, int tid) {
;     ...
;             mx = fmaxf(mx, __shfl_xor(mx, 16)); mx = fmaxf(mx, __shfl_xor(mx, 32));
;             float sum = 0.f;
; #pragma unroll
;             for (int kt = 0; kt < 10; ++kt)
; #pragma unroll
;                 for (int r = 0; r < 4; ++r) { const float p = __builtin_amdgcn_exp2f(s[kt][r] - mx); s[kt][r] = p; sum += p; }
;             sum += __shfl_xor(sum, 16); sum += __shfl_xor(sum, 32);
;             sum += __builtin_amdgcn_exp2f(sink2 - mx);
;             const float inv = 1.0f / sum;
;             f32x4 o[4];
; #pragma unroll
;             for (int dt = 0; dt < 4; ++dt) o[dt] = (f32x4){0.f, 0.f, 0.f, 0.f};
; #pragma unroll
;             for (int kk = 0; kk < 5; ++kk) {
;                 const u32x4 pw = pack8(s[2 * kk], s[2 * kk + 1]);
;                 const bf16x8 pf = __builtin_bit_cast(bf16x8, pw);
; #pragma unroll
;                 for (int dt = 0; dt < 4; ++dt) {
;                     const int d = dt * 16 + fr, sw = ((d >> 3) & 7) << 2, keyA = 16 * (kt0 + 2 * kk) + 4 * fq, keyB = keyA + 16;
;                     const u32x2 va = *(const LAS u32x2*)(Vt + d * VP + ((keyA ^ sw) * 2)), vb = *(const LAS u32x2*)(Vt + d * VP + ((keyB ^ sw) * 2));
;                     const u32x4 vw = (u32x4){va.x, va.y, vb.x, vb.y};
;                     o[dt] = __builtin_amdgcn_mfma_f32_16x16x32_bf16(__builtin_bit_cast(bf16x8, vw), pf, o[dt], 0, 0, 0);
	v_max_f32_e32 v143, v143, v143
	v_max_f32_e32 v142, v142, v143
	ds_bpermute_b32 v143, v92, v142
	s_cmp_eq_u32 s1, 64
	s_waitcnt lgkmcnt(0)
	v_max_f32_e32 v143, v143, v143
	v_max_f32_e32 v142, v142, v143
	v_sub_f32_e32 v68, v68, v142
	v_exp_f32_e32 v68, v68
	v_sub_f32_e32 v69, v69, v142
	v_exp_f32_e32 v69, v69
	v_sub_f32_e32 v70, v70, v142
	v_exp_f32_e32 v70, v70
	v_sub_f32_e32 v71, v71, v142
	v_exp_f32_e32 v71, v71
	v_sub_f32_e32 v64, v64, v142
	v_add_f32_e32 v143, 0, v68
	v_exp_f32_e32 v64, v64
	v_sub_f32_e32 v65, v65, v142
	v_add_f32_e32 v143, v69, v143
	v_exp_f32_e32 v65, v65
	v_sub_f32_e32 v66, v66, v142
	v_add_f32_e32 v143, v70, v143
	v_exp_f32_e32 v66, v66
	v_sub_f32_e32 v67, v67, v142
	v_add_f32_e32 v143, v71, v143
	v_exp_f32_e32 v67, v67
	v_sub_f32_e32 v60, v60, v142
	v_add_f32_e32 v143, v64, v143
	v_exp_f32_e32 v60, v60
	v_sub_f32_e32 v61, v61, v142
	v_add_f32_e32 v143, v65, v143
	v_exp_f32_e32 v61, v61
	v_sub_f32_e32 v62, v62, v142
	v_add_f32_e32 v143, v66, v143
	v_exp_f32_e32 v62, v62
	v_sub_f32_e32 v63, v63, v142
	v_add_f32_e32 v143, v67, v143
	v_exp_f32_e32 v63, v63
	v_sub_f32_e32 v56, v56, v142
	v_add_f32_e32 v143, v60, v143
	v_exp_f32_e32 v56, v56
	v_sub_f32_e32 v57, v57, v142
	v_add_f32_e32 v143, v61, v143
	v_exp_f32_e32 v57, v57
	v_sub_f32_e32 v58, v58, v142
	v_add_f32_e32 v143, v62, v143
	v_exp_f32_e32 v58, v58
	v_sub_f32_e32 v59, v59, v142
	v_add_f32_e32 v143, v63, v143
	v_exp_f32_e32 v59, v59
	v_sub_f32_e32 v52, v52, v142
	v_add_f32_e32 v143, v56, v143
	v_exp_f32_e32 v144, v52
	v_add_f32_e32 v143, v57, v143
	v_add_f32_e32 v143, v58, v143
	v_add_f32_e32 v143, v59, v143
	v_sub_f32_e32 v53, v53, v142
	v_add_f32_e32 v52, v144, v143
	v_exp_f32_e32 v143, v53
	v_sub_f32_e32 v53, v54, v142
	v_exp_f32_e32 v145, v53
	v_sub_f32_e32 v53, v55, v142
	v_exp_f32_e32 v146, v53
	v_sub_f32_e32 v48, v48, v142
	v_exp_f32_e32 v147, v48
	v_sub_f32_e32 v49, v49, v142
	v_add_f32_e32 v52, v143, v52
	v_exp_f32_e32 v148, v49
	v_sub_f32_e32 v49, v50, v142
	v_add_f32_e32 v52, v145, v52
	v_exp_f32_e32 v150, v49
	v_sub_f32_e32 v49, v51, v142
	v_add_f32_e32 v52, v146, v52
	v_exp_f32_e32 v151, v49
	v_sub_f32_e32 v44, v44, v142
	v_add_f32_e32 v48, v147, v52
	v_exp_f32_e32 v152, v44
	v_sub_f32_e32 v45, v45, v142
	v_add_f32_e32 v48, v148, v48
	v_exp_f32_e32 v153, v45
	v_sub_f32_e32 v45, v46, v142
	v_add_f32_e32 v48, v150, v48
	v_exp_f32_e32 v155, v45
	v_sub_f32_e32 v45, v47, v142
	v_add_f32_e32 v48, v151, v48
	v_exp_f32_e32 v157, v45
	v_sub_f32_e32 v40, v40, v142
	v_add_f32_e32 v44, v152, v48
	v_exp_f32_e32 v158, v40
	v_sub_f32_e32 v41, v41, v142
	v_add_f32_e32 v44, v153, v44
	v_exp_f32_e32 v159, v41
	v_sub_f32_e32 v41, v42, v142
	v_add_f32_e32 v44, v155, v44
	v_exp_f32_e32 v160, v41
	v_sub_f32_e32 v41, v43, v142
	v_add_f32_e32 v44, v157, v44
	v_exp_f32_e32 v161, v41
	v_sub_f32_e32 v36, v36, v142
	v_add_f32_e32 v40, v158, v44
	v_exp_f32_e32 v162, v36
	v_sub_f32_e32 v37, v37, v142
	v_add_f32_e32 v40, v159, v40
	v_exp_f32_e32 v165, v37
	v_sub_f32_e32 v37, v38, v142
	v_add_f32_e32 v40, v160, v40
	v_exp_f32_e32 v166, v37
	v_sub_f32_e32 v37, v39, v142
	v_add_f32_e32 v40, v161, v40
	v_exp_f32_e32 v167, v37
	v_sub_f32_e32 v32, v32, v142
	v_add_f32_e32 v36, v162, v40
	v_exp_f32_e32 v168, v32
	v_sub_f32_e32 v33, v33, v142
	v_add_f32_e32 v36, v165, v36
	v_exp_f32_e32 v169, v33
	v_sub_f32_e32 v33, v34, v142
	v_add_f32_e32 v36, v166, v36
	v_exp_f32_e32 v170, v33
	v_sub_f32_e32 v33, v35, v142
	v_add_f32_e32 v36, v167, v36
	v_exp_f32_e32 v171, v33
	v_add_f32_e32 v32, v168, v36
	v_add_f32_e32 v32, v169, v32
	v_add_f32_e32 v32, v170, v32
	v_add_f32_e32 v32, v171, v32
	ds_bpermute_b32 v33, v91, v32
	v_add_u32_e32 v50, 16, v154
	v_bitop3_b32 v36, s25, v93, v76 bitop3:0x36
	v_xor_b32_e32 v38, v50, v93
	v_bitop3_b32 v40, s25, v95, v76 bitop3:0x36
	s_waitcnt lgkmcnt(0)
	v_add_f32_e32 v32, v32, v33
	ds_bpermute_b32 v33, v92, v32
	v_xor_b32_e32 v42, v50, v95
	v_bitop3_b32 v44, s25, v96, v76 bitop3:0x36
	v_xor_b32_e32 v46, v50, v96
	v_bitop3_b32 v48, s25, v97, v76 bitop3:0x36
	s_waitcnt lgkmcnt(0)
	v_add_f32_e32 v32, v32, v33
	v_sub_f32_e32 v33, v141, v142
	v_exp_f32_e32 v33, v33
	v_xor_b32_e32 v50, v50, v97
	v_lshl_add_u32 v36, v36, 1, v94
	v_lshl_add_u32 v38, v38, 1, v94
	v_lshl_add_u32 v40, v40, 1, v94
	v_lshl_add_u32 v42, v42, 1, v94
	v_lshl_add_u32 v44, v44, 1, v94
	v_lshl_add_u32 v46, v46, 1, v94
	v_lshl_add_u32 v48, v48, 1, v94
	v_lshl_add_u32 v50, v50, 1, v94
	v_add_f32_e32 v142, v33, v32
	v_cvt_pk_bf16_f32 v32, v68, v69
	v_cvt_pk_bf16_f32 v33, v70, v71
	v_cvt_pk_bf16_f32 v34, v64, v65
	v_cvt_pk_bf16_f32 v35, v66, v67
	ds_read_b64 v[36:37], v36 offset:36864
	ds_read_b64 v[38:39], v38 offset:36864
	ds_read_b64 v[40:41], v40 offset:45312
	ds_read_b64 v[42:43], v42 offset:45312
	ds_read_b64 v[44:45], v44 offset:53760
	ds_read_b64 v[46:47], v46 offset:53760
	ds_read_b64 v[48:49], v48 offset:62208
	ds_read_b64 v[50:51], v50 offset:62208
	s_waitcnt lgkmcnt(6)
	v_mfma_f32_16x16x32_bf16 v[36:39], v[36:39], v[32:35], 0
	v_bitop3_b32 v52, s29, v93, v76 bitop3:0x36
	v_lshl_add_u32 v52, v52, 1, v94
	s_waitcnt lgkmcnt(4)
	v_mfma_f32_16x16x32_bf16 v[40:43], v[40:43], v[32:35], 0
	s_waitcnt lgkmcnt(2)
	v_mfma_f32_16x16x32_bf16 v[44:47], v[44:47], v[32:35], 0
	s_waitcnt lgkmcnt(0)
	v_mfma_f32_16x16x32_bf16 v[32:35], v[48:51], v[32:35], 0
	v_cvt_pk_bf16_f32 v48, v60, v61
	v_cvt_pk_bf16_f32 v49, v62, v63
	v_cvt_pk_bf16_f32 v50, v56, v57
	v_add_u32_e32 v56, 16, v164
	v_xor_b32_e32 v54, v56, v93
	v_lshl_add_u32 v54, v54, 1, v94
	v_cvt_pk_bf16_f32 v51, v58, v59
	ds_read_b64 v[52:53], v52 offset:36864
	ds_read_b64 v[54:55], v54 offset:36864
	s_waitcnt lgkmcnt(0)
; __device__ __forceinline__ u32x4 pack8(const f32x4 a, const f32x4 b) { u32x4 w; w.x = cvt_pk_bf16(a[0], a[1]); w.y = cvt_pk_bf16(a[2], a[3]); w.z = cvt_pk_bf16(b[0], b[1]); w.w = cvt_pk_bf16(b[2], b[3]); return w; }
; #define LAS __attribute__((address_space(3)))
; __device__ __forceinline__ void attn_phase(LAS unsigned char* lds, const bf16_t* QKVZ, const float* sinks, bf16_t* OG, int G, int bid, int tid) {
;     ...
;             for (int kk = 0; kk < 5; ++kk) {
;                 const u32x4 pw = pack8(s[2 * kk], s[2 * kk + 1]);
;                 const bf16x8 pf = __builtin_bit_cast(bf16x8, pw);
; #pragma unroll
;                 for (int dt = 0; dt < 4; ++dt) {
;                     const int d = dt * 16 + fr, sw = ((d >> 3) & 7) << 2, keyA = 16 * (kt0 + 2 * kk) + 4 * fq, keyB = keyA + 16;
;                     const u32x2 va = *(const LAS u32x2*)(Vt + d * VP + ((keyA ^ sw) * 2)), vb = *(const LAS u32x2*)(Vt + d * VP + ((keyB ^ sw) * 2));
;                     const u32x4 vw = (u32x4){va.x, va.y, vb.x, vb.y};
;                     o[dt] = __builtin_amdgcn_mfma_f32_16x16x32_bf16(__builtin_bit_cast(bf16x8, vw), pf, o[dt], 0, 0, 0);
;                 }
;             }
	v_mfma_f32_16x16x32_bf16 v[36:39], v[52:55], v[48:51], v[36:39]
	v_bitop3_b32 v52, s29, v95, v76 bitop3:0x36
	v_xor_b32_e32 v54, v56, v95
	v_lshl_add_u32 v52, v52, 1, v94
	v_lshl_add_u32 v54, v54, 1, v94
	ds_read_b64 v[52:53], v52 offset:45312
	ds_read_b64 v[54:55], v54 offset:45312
	s_waitcnt lgkmcnt(0)
	v_mfma_f32_16x16x32_bf16 v[40:43], v[52:55], v[48:51], v[40:43]
	v_bitop3_b32 v52, s29, v96, v76 bitop3:0x36
	v_xor_b32_e32 v54, v56, v96
	v_lshl_add_u32 v52, v52, 1, v94
	v_lshl_add_u32 v54, v54, 1, v94
	ds_read_b64 v[52:53], v52 offset:53760
	ds_read_b64 v[54:55], v54 offset:53760
	s_waitcnt lgkmcnt(0)
	v_mfma_f32_16x16x32_bf16 v[44:47], v[52:55], v[48:51], v[44:47]
	v_bitop3_b32 v52, s29, v97, v76 bitop3:0x36
	v_xor_b32_e32 v54, v56, v97
	v_lshl_add_u32 v52, v52, 1, v94
	v_lshl_add_u32 v54, v54, 1, v94
	ds_read_b64 v[52:53], v52 offset:62208
	ds_read_b64 v[54:55], v54 offset:62208
	v_add_u32_e32 v56, 16, v163
	s_waitcnt lgkmcnt(0)
	v_mfma_f32_16x16x32_bf16 v[32:35], v[52:55], v[48:51], v[32:35]
	v_bitop3_b32 v52, s28, v93, v76 bitop3:0x36
	v_xor_b32_e32 v54, v56, v93
	v_lshl_add_u32 v52, v52, 1, v94
	v_lshl_add_u32 v54, v54, 1, v94
	v_cvt_pk_bf16_f32 v48, v144, v143
	v_cvt_pk_bf16_f32 v49, v145, v146
	v_cvt_pk_bf16_f32 v50, v147, v148
	v_cvt_pk_bf16_f32 v51, v150, v151
	ds_read_b64 v[52:53], v52 offset:36864
	ds_read_b64 v[54:55], v54 offset:36864
	s_waitcnt lgkmcnt(0)
	v_mfma_f32_16x16x32_bf16 v[36:39], v[52:55], v[48:51], v[36:39]
	v_bitop3_b32 v52, s28, v95, v76 bitop3:0x36
	v_xor_b32_e32 v54, v56, v95
	v_lshl_add_u32 v52, v52, 1, v94
	v_lshl_add_u32 v54, v54, 1, v94
	ds_read_b64 v[52:53], v52 offset:45312
	ds_read_b64 v[54:55], v54 offset:45312
	s_waitcnt lgkmcnt(0)
	v_mfma_f32_16x16x32_bf16 v[40:43], v[52:55], v[48:51], v[40:43]
	v_bitop3_b32 v52, s28, v96, v76 bitop3:0x36
	v_xor_b32_e32 v54, v56, v96
	v_lshl_add_u32 v52, v52, 1, v94
	v_lshl_add_u32 v54, v54, 1, v94
	ds_read_b64 v[52:53], v52 offset:53760
	ds_read_b64 v[54:55], v54 offset:53760
	s_waitcnt lgkmcnt(0)
	v_mfma_f32_16x16x32_bf16 v[44:47], v[52:55], v[48:51], v[44:47]
	v_bitop3_b32 v52, s28, v97, v76 bitop3:0x36
	v_xor_b32_e32 v54, v56, v97
	v_lshl_add_u32 v52, v52, 1, v94
	v_lshl_add_u32 v54, v54, 1, v94
	ds_read_b64 v[52:53], v52 offset:62208
	ds_read_b64 v[54:55], v54 offset:62208
	v_add_u32_e32 v56, 16, v156
	s_waitcnt lgkmcnt(0)
	v_mfma_f32_16x16x32_bf16 v[32:35], v[52:55], v[48:51], v[32:35]
	v_bitop3_b32 v52, s27, v93, v76 bitop3:0x36
	v_xor_b32_e32 v54, v56, v93
	v_lshl_add_u32 v52, v52, 1, v94
	v_lshl_add_u32 v54, v54, 1, v94
	v_cvt_pk_bf16_f32 v48, v152, v153
	v_cvt_pk_bf16_f32 v49, v155, v157
	v_cvt_pk_bf16_f32 v50, v158, v159
	v_cvt_pk_bf16_f32 v51, v160, v161
	ds_read_b64 v[52:53], v52 offset:36864
	ds_read_b64 v[54:55], v54 offset:36864
	s_waitcnt lgkmcnt(0)
	v_mfma_f32_16x16x32_bf16 v[36:39], v[52:55], v[48:51], v[36:39]
	v_bitop3_b32 v52, s27, v95, v76 bitop3:0x36
	v_xor_b32_e32 v54, v56, v95
	v_lshl_add_u32 v52, v52, 1, v94
	v_lshl_add_u32 v54, v54, 1, v94
	ds_read_b64 v[52:53], v52 offset:45312
	ds_read_b64 v[54:55], v54 offset:45312
	s_waitcnt lgkmcnt(0)
	v_mfma_f32_16x16x32_bf16 v[40:43], v[52:55], v[48:51], v[40:43]
	v_bitop3_b32 v52, s27, v96, v76 bitop3:0x36
	v_xor_b32_e32 v54, v56, v96
	v_lshl_add_u32 v52, v52, 1, v94
	v_lshl_add_u32 v54, v54, 1, v94
	ds_read_b64 v[52:53], v52 offset:53760
	ds_read_b64 v[54:55], v54 offset:53760
	s_waitcnt lgkmcnt(0)
	v_mfma_f32_16x16x32_bf16 v[52:55], v[52:55], v[48:51], v[44:47]
	s_nop 2
	v_bitop3_b32 v44, s27, v97, v76 bitop3:0x36
	v_xor_b32_e32 v46, v56, v97
	v_lshl_add_u32 v44, v44, 1, v94
	v_lshl_add_u32 v46, v46, 1, v94
	ds_read_b64 v[44:45], v44 offset:62208
	ds_read_b64 v[46:47], v46 offset:62208
	v_add_u32_e32 v56, 16, v149
	s_waitcnt lgkmcnt(0)
	v_mfma_f32_16x16x32_bf16 v[32:35], v[44:47], v[48:51], v[32:35]
	v_bitop3_b32 v44, s26, v93, v76 bitop3:0x36
	v_xor_b32_e32 v46, v56, v93
	v_lshl_add_u32 v44, v44, 1, v94
	v_lshl_add_u32 v46, v46, 1, v94
	v_cvt_pk_bf16_f32 v48, v162, v165
	v_cvt_pk_bf16_f32 v49, v166, v167
	v_cvt_pk_bf16_f32 v50, v168, v169
	v_cvt_pk_bf16_f32 v51, v170, v171
	ds_read_b64 v[44:45], v44 offset:36864
	ds_read_b64 v[46:47], v46 offset:36864
	s_waitcnt lgkmcnt(0)
	v_mfma_f32_16x16x32_bf16 v[44:47], v[44:47], v[48:51], v[36:39]
	s_nop 2
	v_bitop3_b32 v36, s26, v95, v76 bitop3:0x36
	v_xor_b32_e32 v38, v56, v95
	v_lshl_add_u32 v36, v36, 1, v94
	v_lshl_add_u32 v38, v38, 1, v94
	ds_read_b64 v[36:37], v36 offset:45312
	ds_read_b64 v[38:39], v38 offset:45312
	s_waitcnt lgkmcnt(0)
	v_mfma_f32_16x16x32_bf16 v[40:43], v[36:39], v[48:51], v[40:43]
	v_bitop3_b32 v36, s26, v96, v76 bitop3:0x36
	v_xor_b32_e32 v38, v56, v96
	v_lshl_add_u32 v36, v36, 1, v94
	v_lshl_add_u32 v38, v38, 1, v94
	ds_read_b64 v[36:37], v36 offset:53760
	ds_read_b64 v[38:39], v38 offset:53760
	s_waitcnt lgkmcnt(0)
	v_mfma_f32_16x16x32_bf16 v[36:39], v[36:39], v[48:51], v[52:55]
	s_nop 2
	v_bitop3_b32 v52, s26, v97, v76 bitop3:0x36
	v_xor_b32_e32 v54, v56, v97
	v_lshl_add_u32 v52, v52, 1, v94
	v_lshl_add_u32 v54, v54, 1, v94
	ds_read_b64 v[52:53], v52 offset:62208
	ds_read_b64 v[54:55], v54 offset:62208
	s_waitcnt lgkmcnt(0)
; __device__ __forceinline__ unsigned cvt_pk_bf16(float lo, float hi) { unsigned r; asm volatile("v_cvt_pk_bf16_f32 %0, %1, %2" : "=v"(r) : "v"(lo), "v"(hi)); return r; }
; __device__ __forceinline__ float bflo(unsigned w) { return __uint_as_float(w << 16); }
; __device__ __forceinline__ float bfhi(unsigned w) { return __uint_as_float(w & 0xffff0000u); }
; __device__ __forceinline__ float fsigmoid(float x) { return __builtin_amdgcn_rcpf(1.0f + __expf(-x)); }
; #define LAS __attribute__((address_space(3)))
; __device__ __forceinline__ void attn_phase(LAS unsigned char* lds, const bf16_t* QKVZ, const float* sinks, bf16_t* OG, int G, int bid, int tid) {
;     ...
;             const float inv = 1.0f / sum;
;             f32x4 o[4];
; #pragma unroll
;             for (int dt = 0; dt < 4; ++dt) o[dt] = (f32x4){0.f, 0.f, 0.f, 0.f};
; #pragma unroll
;             for (int kk = 0; kk < 5; ++kk) {
;                 const u32x4 pw = pack8(s[2 * kk], s[2 * kk + 1]);
;                 const bf16x8 pf = __builtin_bit_cast(bf16x8, pw);
; #pragma unroll
;                 for (int dt = 0; dt < 4; ++dt) {
;                     const int d = dt * 16 + fr, sw = ((d >> 3) & 7) << 2, keyA = 16 * (kt0 + 2 * kk) + 4 * fq, keyB = keyA + 16;
;                     const u32x2 va = *(const LAS u32x2*)(Vt + d * VP + ((keyA ^ sw) * 2)), vb = *(const LAS u32x2*)(Vt + d * VP + ((keyB ^ sw) * 2));
;                     const u32x4 vw = (u32x4){va.x, va.y, vb.x, vb.y};
;                     o[dt] = __builtin_amdgcn_mfma_f32_16x16x32_bf16(__builtin_bit_cast(bf16x8, vw), pf, o[dt], 0, 0, 0);
;                 }
;             }
;             const bf16_t* zp = QKVZ + row * ATT_IN + 1536 + h * 64 + 4 * fq;
;             bf16_t* op = OG + row * D + h * 64 + 4 * fq;
; #pragma unroll
;             for (int dt = 0; dt < 4; ++dt) {
;                 const u32x2 zw = *(const u32x2*)(zp + dt * 16);
;                 const float z0 = bflo(zw.x), z1 = bfhi(zw.x), z2 = bflo(zw.y), z3 = bfhi(zw.y);
;                 const float r0 = o[dt][0] * inv * z0 * fsigmoid(z0), r1 = o[dt][1] * inv * z1 * fsigmoid(z1), r2 = o[dt][2] * inv * z2 * fsigmoid(z2), r3 = o[dt][3] * inv * z3 * fsigmoid(z3);
;                 u32x2 w; w.x = cvt_pk_bf16(r0, r1); w.y = cvt_pk_bf16(r2, r3);
;                 *(u32x2*)(op + dt * 16) = w;
;             }
;         }
	v_mfma_f32_16x16x32_bf16 v[32:35], v[52:55], v[48:51], v[32:35]
	v_div_scale_f32 v48, s[26:27], v142, v142, 1.0
	v_rcp_f32_e32 v49, v48
	s_nop 0
	v_fma_f32 v50, -v48, v49, 1.0
	v_fmac_f32_e32 v49, v50, v49
	v_div_scale_f32 v50, vcc, 1.0, v142, 1.0
	v_mul_f32_e32 v51, v50, v49
	v_fma_f32 v52, -v48, v51, v50
	v_fmac_f32_e32 v51, v52, v49
	v_fma_f32 v48, -v48, v51, v50
	v_div_fmas_f32 v48, v48, v49, v51
	v_div_fixup_f32 v52, v48, v142, 1.0
	v_lshlrev_b32_e32 v48, 1, v76
	v_mov_b32_e32 v49, v73
	v_lshl_add_u64 v[50:51], v[84:85], 0, v[48:49]
	v_mul_f32_e32 v44, v52, v44
	v_mul_f32_e32 v45, v52, v45
	v_mul_f32_e32 v46, v52, v46
	v_mul_f32_e32 v47, v52, v47
	v_lshlrev_b64 v[48:49], 11, v[82:83]
	v_lshl_add_u64 v[48:49], v[80:81], 0, v[48:49]
	v_mul_f32_e32 v41, v52, v41
	v_mul_f32_e32 v40, v52, v40
	v_mul_f32_e32 v42, v52, v42
	v_mul_f32_e32 v43, v52, v43
	v_mul_f32_e32 v37, v52, v37
	v_mul_f32_e32 v36, v52, v36
	v_mul_f32_e32 v38, v52, v38
	v_mul_f32_e32 v39, v52, v39
	v_mul_f32_e32 v33, v52, v33
	v_mul_f32_e32 v32, v52, v32
	v_mul_f32_e32 v34, v52, v34
	v_mul_f32_e32 v35, v52, v35
	s_waitcnt vmcnt(0)
	v_mov_b64_e32 v[54:55], v[200:201]
	v_lshlrev_b32_e32 v53, 16, v54
	v_mul_f32_e32 v44, v44, v53
	v_mul_f32_e32 v53, 0xbfb8aa3b, v53
	v_exp_f32_e32 v53, v53
	v_and_b32_e32 v54, 0xffff0000, v54
	v_lshlrev_b32_e32 v56, 16, v55
	v_mul_f32_e32 v45, v45, v54
	v_add_f32_e32 v53, 1.0, v53
	v_rcp_f32_e32 v53, v53
	v_and_b32_e32 v55, 0xffff0000, v55
	v_mul_f32_e32 v46, v46, v56
	v_mul_f32_e32 v47, v47, v55
	v_mul_f32_e32 v44, v44, v53
	v_mul_f32_e32 v53, 0xbfb8aa3b, v54
	v_exp_f32_e32 v53, v53
	s_nop 0
	v_add_f32_e32 v53, 1.0, v53
	v_rcp_f32_e32 v53, v53
	s_nop 0
	v_mul_f32_e32 v45, v45, v53
	v_mul_f32_e32 v53, 0xbfb8aa3b, v56
	v_exp_f32_e32 v53, v53
	v_cvt_pk_bf16_f32 v44, v44, v45
	s_nop 0
	v_add_f32_e32 v53, 1.0, v53
	v_rcp_f32_e32 v53, v53
	s_nop 0
	v_mul_f32_e32 v46, v46, v53
	v_mul_f32_e32 v53, 0xbfb8aa3b, v55
	v_exp_f32_e32 v53, v53
	s_nop 0
	v_add_f32_e32 v53, 1.0, v53
	v_rcp_f32_e32 v53, v53
	s_nop 0
	v_mul_f32_e32 v47, v47, v53
	v_cvt_pk_bf16_f32 v45, v46, v47
	global_store_dwordx2 v[48:49], v[44:45], off
	s_nop 1
	v_mov_b64_e32 v[44:45], v[202:203]
	v_lshlrev_b32_e32 v46, 16, v44
	v_and_b32_e32 v44, 0xffff0000, v44
	v_mul_f32_e32 v41, v41, v44
	v_mul_f32_e32 v44, 0xbfb8aa3b, v44
	v_exp_f32_e32 v44, v44
	v_lshlrev_b32_e32 v47, 16, v45
	v_and_b32_e32 v45, 0xffff0000, v45
	v_mul_f32_e32 v40, v40, v46
	v_add_f32_e32 v44, 1.0, v44
	v_rcp_f32_e32 v44, v44
	v_mul_f32_e32 v46, 0xbfb8aa3b, v46
	v_mul_f32_e32 v42, v42, v47
	v_exp_f32_e32 v46, v46
	v_mul_f32_e32 v41, v41, v44
	v_mul_f32_e32 v44, 0xbfb8aa3b, v47
	v_exp_f32_e32 v44, v44
	v_add_f32_e32 v46, 1.0, v46
	v_rcp_f32_e32 v46, v46
	v_mul_f32_e32 v43, v43, v45
	v_add_f32_e32 v44, 1.0, v44
	v_rcp_f32_e32 v44, v44
	v_mul_f32_e32 v40, v40, v46
	v_cvt_pk_bf16_f32 v40, v40, v41
	v_mul_f32_e32 v42, v42, v44
	v_mul_f32_e32 v44, 0xbfb8aa3b, v45
	v_exp_f32_e32 v44, v44
	s_nop 0
	v_add_f32_e32 v44, 1.0, v44
	v_rcp_f32_e32 v44, v44
	s_nop 0
	v_mul_f32_e32 v43, v43, v44
	v_cvt_pk_bf16_f32 v41, v42, v43
	global_store_dwordx2 v[48:49], v[40:41], off offset:32
	s_nop 1
	v_mov_b64_e32 v[40:41], v[204:205]
	v_lshlrev_b32_e32 v42, 16, v40
	v_and_b32_e32 v40, 0xffff0000, v40
	v_mul_f32_e32 v37, v37, v40
	v_mul_f32_e32 v40, 0xbfb8aa3b, v40
	v_exp_f32_e32 v40, v40
	v_lshlrev_b32_e32 v43, 16, v41
	v_and_b32_e32 v41, 0xffff0000, v41
	v_mul_f32_e32 v36, v36, v42
	v_add_f32_e32 v40, 1.0, v40
	v_rcp_f32_e32 v40, v40
	v_mul_f32_e32 v42, 0xbfb8aa3b, v42
	v_mul_f32_e32 v38, v38, v43
	v_exp_f32_e32 v42, v42
	v_mul_f32_e32 v37, v37, v40
	v_mul_f32_e32 v40, 0xbfb8aa3b, v43
	v_exp_f32_e32 v40, v40
	v_add_f32_e32 v42, 1.0, v42
	v_rcp_f32_e32 v42, v42
	v_mul_f32_e32 v39, v39, v41
	v_add_f32_e32 v40, 1.0, v40
	v_rcp_f32_e32 v40, v40
	v_mul_f32_e32 v36, v36, v42
	v_cvt_pk_bf16_f32 v36, v36, v37
	v_mul_f32_e32 v38, v38, v40
	v_mul_f32_e32 v40, 0xbfb8aa3b, v41
	v_exp_f32_e32 v40, v40
	s_nop 0
	v_add_f32_e32 v40, 1.0, v40
	v_rcp_f32_e32 v40, v40
	s_nop 0
	v_mul_f32_e32 v39, v39, v40
	v_cvt_pk_bf16_f32 v37, v38, v39
	global_store_dwordx2 v[48:49], v[36:37], off offset:64
	s_nop 1
	v_mov_b64_e32 v[36:37], v[206:207]
	v_lshlrev_b32_e32 v38, 16, v36
	v_and_b32_e32 v36, 0xffff0000, v36
	v_mul_f32_e32 v33, v33, v36
	v_mul_f32_e32 v36, 0xbfb8aa3b, v36
	v_exp_f32_e32 v36, v36
	v_lshlrev_b32_e32 v39, 16, v37
	v_and_b32_e32 v37, 0xffff0000, v37
	v_mul_f32_e32 v32, v32, v38
	v_add_f32_e32 v36, 1.0, v36
	v_rcp_f32_e32 v36, v36
	v_mul_f32_e32 v38, 0xbfb8aa3b, v38
	v_mul_f32_e32 v34, v34, v39
	v_exp_f32_e32 v38, v38
	v_mul_f32_e32 v33, v33, v36
	v_mul_f32_e32 v36, 0xbfb8aa3b, v39
	v_exp_f32_e32 v36, v36
	v_add_f32_e32 v38, 1.0, v38
	v_rcp_f32_e32 v38, v38
	v_mul_f32_e32 v35, v35, v37
	v_add_f32_e32 v36, 1.0, v36
	v_rcp_f32_e32 v36, v36
	v_mul_f32_e32 v32, v32, v38
	v_cvt_pk_bf16_f32 v32, v32, v33
	v_mul_f32_e32 v34, v34, v36
	v_mul_f32_e32 v36, 0xbfb8aa3b, v37
	v_exp_f32_e32 v36, v36
	s_nop 0
	v_add_f32_e32 v36, 1.0, v36
	v_rcp_f32_e32 v36, v36
	s_nop 0
	v_mul_f32_e32 v35, v35, v36
	v_cvt_pk_bf16_f32 v33, v34, v35
	global_store_dwordx2 v[48:49], v[32:33], off offset:96
	s_cbranch_scc0 .LBB0_246
	s_add_i32 s16, s16, s21
	s_and_b64 vcc, exec, s[10:11]
	s_mov_b32 s12, s24
	s_cbranch_vccz .LBB0_235
